# fused final epilogue: gain vector loaded once (hoisted before the exchange wait) instead of reloaded per store round; per-round vmcnt waits removed
# speedup vs baseline: 1.0379x; 1.0081x over previous
; __device__ __forceinline__ void epi_final(f32x4 (&acc)[2][2][4][2], const Unit& u, int wr, int wc, int fr, int fq, const EpiArgs& E, LAS float* rt) {
;     ...
;     if (wid == 0) {
;         unsigned sp = 0;
;         while ((unsigned)__builtin_amdgcn_readfirstlane(__hip_atomic_load(cw, __ATOMIC_RELAXED, __HIP_MEMORY_SCOPE_AGENT)) < 32u) { __builtin_amdgcn_s_sleep(2); if (++sp > (1u << 20)) break; }
;     }
;     ...
;                 const f32x4 g0 = *(const f32x4*)(E.gfin + col), g1 = *(const f32x4*)(E.gfin + col + 4);
.LBB0_1434:
	v_lshlrev_b64 v[188:189], 2, v[132:133]
	v_lshl_add_u64 v[188:189], s[24:25], 0, v[188:189]
	global_load_dwordx4 v[172:175], v[188:189], off
	global_load_dwordx4 v[176:179], v[188:189], off offset:16
	global_load_dwordx4 v[180:183], v[188:189], off offset:512
	global_load_dwordx4 v[184:187], v[188:189], off offset:528
	s_cmp_gt_u32 s9, 63
	s_cbranch_scc1 .LBB0_1439
	s_mov_b32 s6, 0x100001
	v_mov_b32_e32 v148, 0
	s_branch .LBB0_1437

; __device__ __forceinline__ void epi_final(f32x4 (&acc)[2][2][4][2], const Unit& u, int wr, int wc, int fr, int fq, const EpiArgs& E, LAS float* rt) {
;     ...
; #pragma unroll
;     for (int ai = 0; ai < 2; ++ai)
; #pragma unroll
;         for (int m = 0; m < 4; ++m) { const int row = rowb + ai * HALF + m * 16; const float r = rt[ai * HALF + wr * 64 + m * 16 + fr];
; #pragma unroll
;             for (int bj = 0; bj < 2; ++bj) { const int col = u.pn * BM + bj * HALF + wc * 32 + fq * 8;
;                 const f32x4 g0 = *(const f32x4*)(E.gfin + col), g1 = *(const f32x4*)(E.gfin + col + 4);
;                 __builtin_nontemporal_store(acc[ai][bj][m][0] * r * g0, (f32x4*)(E.yout + (size_t)row * 1024 + col));
;                 __builtin_nontemporal_store(acc[ai][bj][m][1] * r * g1, (f32x4*)(E.yout + (size_t)row * 1024 + col + 4)); } }
.LBB0_1441:
	s_or_b64 exec, exec, s[0:1]
	v_lshlrev_b64 v[148:149], 2, v[132:133]
	v_lshl_add_u64 v[132:133], s[24:25], 0, v[148:149]
	s_waitcnt lgkmcnt(0)
	s_barrier
	s_waitcnt vmcnt(0)
	s_lshl_b32 s0, s47, 2
	s_add_i32 s0, s0, 0
	v_lshl_add_u32 v1, v1, 2, s0
	v_add_u32_e32 v1, 0x20010, v1
	ds_read2_b32 v[158:159], v1 offset1:16
	v_lshlrev_b64 v[130:131], 12, v[130:131]
	v_lshl_add_u64 v[130:131], s[28:29], 0, v[130:131]
	v_lshl_add_u64 v[130:131], v[130:131], 0, v[148:149]
	s_waitcnt lgkmcnt(0)
	v_pk_mul_f32 v[128:129], v[128:129], v[158:159] op_sel_hi:[1,0]
	v_pk_mul_f32 v[126:127], v[126:127], v[158:159] op_sel_hi:[1,0]
	v_pk_mul_f32 v[160:161], v[124:125], v[158:159] op_sel_hi:[1,0]
	v_pk_mul_f32 v[162:163], v[122:123], v[158:159] op_sel_hi:[1,0]
	v_pk_mul_f32 v[120:121], v[120:121], v[158:159] op_sel_hi:[1,0]
	v_pk_mul_f32 v[118:119], v[118:119], v[158:159] op_sel_hi:[1,0]
	v_pk_mul_f32 v[124:125], v[174:175], v[128:129]
	v_pk_mul_f32 v[122:123], v[172:173], v[126:127]
	v_pk_mul_f32 v[128:129], v[178:179], v[160:161]
	v_pk_mul_f32 v[126:127], v[176:177], v[162:163]
	global_store_dwordx4 v[130:131], v[122:125], off nt
	global_store_dwordx4 v[130:131], v[126:129], off offset:16 nt
	v_pk_mul_f32 v[150:151], v[116:117], v[158:159] op_sel_hi:[1,0]
	v_pk_mul_f32 v[152:153], v[114:115], v[158:159] op_sel_hi:[1,0]
	v_pk_mul_f32 v[116:117], v[120:121], v[182:183]
	v_pk_mul_f32 v[114:115], v[118:119], v[180:181]
	v_pk_mul_f32 v[120:121], v[150:151], v[186:187]
	v_pk_mul_f32 v[118:119], v[152:153], v[184:185]
	global_store_dwordx4 v[130:131], v[114:117], off offset:512 nt
	global_store_dwordx4 v[130:131], v[118:121], off offset:528 nt
	v_lshlrev_b64 v[122:123], 12, v[134:135]
	v_mov_b32_e32 v124, v159
	v_lshl_add_u64 v[122:123], s[28:29], 0, v[122:123]
	v_pk_mul_f32 v[112:113], v[112:113], v[124:125] op_sel_hi:[1,0]
	v_pk_mul_f32 v[126:127], v[136:137], v[124:125] op_sel_hi:[1,0]
	v_lshl_add_u64 v[122:123], v[122:123], 0, v[148:149]
	v_pk_mul_f32 v[128:129], v[108:109], v[124:125] op_sel_hi:[1,0]
	v_pk_mul_f32 v[130:131], v[106:107], v[124:125] op_sel_hi:[1,0]
	v_pk_mul_f32 v[104:105], v[104:105], v[124:125] op_sel_hi:[1,0]
	v_pk_mul_f32 v[102:103], v[102:103], v[124:125] op_sel_hi:[1,0]
	v_pk_mul_f32 v[108:109], v[174:175], v[112:113]
	v_pk_mul_f32 v[106:107], v[172:173], v[126:127]
	v_pk_mul_f32 v[114:115], v[178:179], v[128:129]
	v_pk_mul_f32 v[112:113], v[176:177], v[130:131]
	global_store_dwordx4 v[122:123], v[106:109], off nt
	global_store_dwordx4 v[122:123], v[112:115], off offset:16 nt
	v_pk_mul_f32 v[116:117], v[100:101], v[124:125] op_sel_hi:[1,0]
	v_pk_mul_f32 v[118:119], v[98:99], v[124:125] op_sel_hi:[1,0]
	v_pk_mul_f32 v[100:101], v[104:105], v[182:183]
	v_pk_mul_f32 v[98:99], v[102:103], v[180:181]
	v_pk_mul_f32 v[104:105], v[116:117], v[186:187]
	v_pk_mul_f32 v[102:103], v[118:119], v[184:185]
	global_store_dwordx4 v[122:123], v[98:101], off offset:512 nt
	global_store_dwordx4 v[122:123], v[102:105], off offset:528 nt
	ds_read2_b32 v[106:107], v1 offset0:32 offset1:48
	v_lshlrev_b64 v[108:109], 12, v[110:111]
	v_lshl_add_u64 v[108:109], s[28:29], 0, v[108:109]
	v_lshl_add_u64 v[108:109], v[108:109], 0, v[148:149]
	s_waitcnt lgkmcnt(0)
	v_pk_mul_f32 v[96:97], v[96:97], v[106:107] op_sel_hi:[1,0]
	v_pk_mul_f32 v[94:95], v[94:95], v[106:107] op_sel_hi:[1,0]
	v_pk_mul_f32 v[110:111], v[92:93], v[106:107] op_sel_hi:[1,0]
	v_pk_mul_f32 v[112:113], v[90:91], v[106:107] op_sel_hi:[1,0]
	v_pk_mul_f32 v[88:89], v[88:89], v[106:107] op_sel_hi:[1,0]
	v_pk_mul_f32 v[86:87], v[86:87], v[106:107] op_sel_hi:[1,0]
	v_pk_mul_f32 v[92:93], v[174:175], v[96:97]
	v_pk_mul_f32 v[90:91], v[172:173], v[94:95]
	v_pk_mul_f32 v[96:97], v[178:179], v[110:111]
	v_pk_mul_f32 v[94:95], v[176:177], v[112:113]
	global_store_dwordx4 v[108:109], v[90:93], off nt
	global_store_dwordx4 v[108:109], v[94:97], off offset:16 nt
	v_pk_mul_f32 v[98:99], v[84:85], v[106:107] op_sel_hi:[1,0]
	v_pk_mul_f32 v[100:101], v[82:83], v[106:107] op_sel_hi:[1,0]
	v_pk_mul_f32 v[84:85], v[88:89], v[182:183]
	v_pk_mul_f32 v[82:83], v[86:87], v[180:181]
	v_pk_mul_f32 v[88:89], v[98:99], v[186:187]
	v_pk_mul_f32 v[86:87], v[100:101], v[184:185]
	global_store_dwordx4 v[108:109], v[82:85], off offset:512 nt
	global_store_dwordx4 v[108:109], v[86:89], off offset:528 nt
	v_lshlrev_b64 v[90:91], 12, v[138:139]
	v_mov_b32_e32 v92, v107
	v_lshl_add_u64 v[90:91], s[28:29], 0, v[90:91]
	v_pk_mul_f32 v[80:81], v[80:81], v[92:93] op_sel_hi:[1,0]
	v_pk_mul_f32 v[94:95], v[140:141], v[92:93] op_sel_hi:[1,0]
	v_lshl_add_u64 v[90:91], v[90:91], 0, v[148:149]
	v_pk_mul_f32 v[96:97], v[76:77], v[92:93] op_sel_hi:[1,0]
	v_pk_mul_f32 v[98:99], v[74:75], v[92:93] op_sel_hi:[1,0]
	v_pk_mul_f32 v[72:73], v[72:73], v[92:93] op_sel_hi:[1,0]
	v_pk_mul_f32 v[70:71], v[70:71], v[92:93] op_sel_hi:[1,0]
	v_pk_mul_f32 v[76:77], v[174:175], v[80:81]
	v_pk_mul_f32 v[74:75], v[172:173], v[94:95]
	v_pk_mul_f32 v[82:83], v[178:179], v[96:97]
	v_pk_mul_f32 v[80:81], v[176:177], v[98:99]
	global_store_dwordx4 v[90:91], v[74:77], off nt
	global_store_dwordx4 v[90:91], v[80:83], off offset:16 nt
	v_pk_mul_f32 v[84:85], v[68:69], v[92:93] op_sel_hi:[1,0]
	v_pk_mul_f32 v[86:87], v[66:67], v[92:93] op_sel_hi:[1,0]
	v_pk_mul_f32 v[68:69], v[72:73], v[182:183]
	v_pk_mul_f32 v[66:67], v[70:71], v[180:181]
	v_pk_mul_f32 v[72:73], v[84:85], v[186:187]
	v_pk_mul_f32 v[70:71], v[86:87], v[184:185]
	global_store_dwordx4 v[90:91], v[66:69], off offset:512 nt
	global_store_dwordx4 v[90:91], v[70:73], off offset:528 nt
	ds_read2_b32 v[74:75], v1 offset0:128 offset1:144
	v_lshlrev_b64 v[76:77], 12, v[78:79]
	v_lshl_add_u64 v[76:77], s[28:29], 0, v[76:77]
	v_lshl_add_u64 v[76:77], v[76:77], 0, v[148:149]
	s_waitcnt lgkmcnt(0)
; __device__ __forceinline__ void epi_final(f32x4 (&acc)[2][2][4][2], const Unit& u, int wr, int wc, int fr, int fq, const EpiArgs& E, LAS float* rt) {
;     ...
; #pragma unroll
;     for (int ai = 0; ai < 2; ++ai)
; #pragma unroll
;         for (int m = 0; m < 4; ++m) { const int row = rowb + ai * HALF + m * 16; const float r = rt[ai * HALF + wr * 64 + m * 16 + fr];
; #pragma unroll
;             for (int bj = 0; bj < 2; ++bj) { const int col = u.pn * BM + bj * HALF + wc * 32 + fq * 8;
;                 const f32x4 g0 = *(const f32x4*)(E.gfin + col), g1 = *(const f32x4*)(E.gfin + col + 4);
;                 __builtin_nontemporal_store(acc[ai][bj][m][0] * r * g0, (f32x4*)(E.yout + (size_t)row * 1024 + col));
;                 __builtin_nontemporal_store(acc[ai][bj][m][1] * r * g1, (f32x4*)(E.yout + (size_t)row * 1024 + col + 4)); } }
	v_pk_mul_f32 v[64:65], v[64:65], v[74:75] op_sel_hi:[1,0]
	v_pk_mul_f32 v[62:63], v[62:63], v[74:75] op_sel_hi:[1,0]
	v_pk_mul_f32 v[78:79], v[60:61], v[74:75] op_sel_hi:[1,0]
	v_pk_mul_f32 v[80:81], v[58:59], v[74:75] op_sel_hi:[1,0]
	v_pk_mul_f32 v[56:57], v[56:57], v[74:75] op_sel_hi:[1,0]
	v_pk_mul_f32 v[54:55], v[54:55], v[74:75] op_sel_hi:[1,0]
	v_pk_mul_f32 v[60:61], v[174:175], v[64:65]
	v_pk_mul_f32 v[58:59], v[172:173], v[62:63]
	v_pk_mul_f32 v[64:65], v[178:179], v[78:79]
	v_pk_mul_f32 v[62:63], v[176:177], v[80:81]
	global_store_dwordx4 v[76:77], v[58:61], off nt
	global_store_dwordx4 v[76:77], v[62:65], off offset:16 nt
	v_pk_mul_f32 v[66:67], v[52:53], v[74:75] op_sel_hi:[1,0]
	v_pk_mul_f32 v[68:69], v[50:51], v[74:75] op_sel_hi:[1,0]
	v_pk_mul_f32 v[52:53], v[56:57], v[182:183]
	v_pk_mul_f32 v[50:51], v[54:55], v[180:181]
	v_pk_mul_f32 v[56:57], v[66:67], v[186:187]
	v_pk_mul_f32 v[54:55], v[68:69], v[184:185]
	global_store_dwordx4 v[76:77], v[50:53], off offset:512 nt
	global_store_dwordx4 v[76:77], v[54:57], off offset:528 nt
	v_lshlrev_b64 v[58:59], 12, v[142:143]
	v_mov_b32_e32 v60, v75
	v_lshl_add_u64 v[58:59], s[28:29], 0, v[58:59]
	v_pk_mul_f32 v[48:49], v[48:49], v[60:61] op_sel_hi:[1,0]
	v_pk_mul_f32 v[62:63], v[144:145], v[60:61] op_sel_hi:[1,0]
	v_lshl_add_u64 v[58:59], v[58:59], 0, v[148:149]
	v_pk_mul_f32 v[64:65], v[44:45], v[60:61] op_sel_hi:[1,0]
	v_pk_mul_f32 v[66:67], v[42:43], v[60:61] op_sel_hi:[1,0]
	v_pk_mul_f32 v[40:41], v[40:41], v[60:61] op_sel_hi:[1,0]
	v_pk_mul_f32 v[38:39], v[38:39], v[60:61] op_sel_hi:[1,0]
	v_pk_mul_f32 v[44:45], v[174:175], v[48:49]
	v_pk_mul_f32 v[42:43], v[172:173], v[62:63]
	v_pk_mul_f32 v[50:51], v[178:179], v[64:65]
	v_pk_mul_f32 v[48:49], v[176:177], v[66:67]
	global_store_dwordx4 v[58:59], v[42:45], off nt
	global_store_dwordx4 v[58:59], v[48:51], off offset:16 nt
	v_pk_mul_f32 v[52:53], v[36:37], v[60:61] op_sel_hi:[1,0]
	v_pk_mul_f32 v[54:55], v[34:35], v[60:61] op_sel_hi:[1,0]
	v_pk_mul_f32 v[36:37], v[40:41], v[182:183]
	v_pk_mul_f32 v[34:35], v[38:39], v[180:181]
	v_pk_mul_f32 v[40:41], v[52:53], v[186:187]
	v_pk_mul_f32 v[38:39], v[54:55], v[184:185]
	global_store_dwordx4 v[58:59], v[34:37], off offset:512 nt
	global_store_dwordx4 v[58:59], v[38:41], off offset:528 nt
	ds_read2_b32 v[42:43], v1 offset0:160 offset1:176
	v_lshlrev_b64 v[44:45], 12, v[46:47]
	v_lshl_add_u64 v[44:45], s[28:29], 0, v[44:45]
	v_lshl_add_u64 v[44:45], v[44:45], 0, v[148:149]
	s_waitcnt lgkmcnt(0)
	v_pk_mul_f32 v[32:33], v[32:33], v[42:43] op_sel_hi:[1,0]
	v_pk_mul_f32 v[30:31], v[30:31], v[42:43] op_sel_hi:[1,0]
	v_pk_mul_f32 v[46:47], v[28:29], v[42:43] op_sel_hi:[1,0]
	v_pk_mul_f32 v[48:49], v[26:27], v[42:43] op_sel_hi:[1,0]
	v_pk_mul_f32 v[24:25], v[24:25], v[42:43] op_sel_hi:[1,0]
	v_pk_mul_f32 v[22:23], v[22:23], v[42:43] op_sel_hi:[1,0]
	v_pk_mul_f32 v[28:29], v[174:175], v[32:33]
	v_pk_mul_f32 v[26:27], v[172:173], v[30:31]
	v_pk_mul_f32 v[32:33], v[178:179], v[46:47]
	v_pk_mul_f32 v[30:31], v[176:177], v[48:49]
	global_store_dwordx4 v[44:45], v[26:29], off nt
	global_store_dwordx4 v[44:45], v[30:33], off offset:16 nt
	v_pk_mul_f32 v[34:35], v[20:21], v[42:43] op_sel_hi:[1,0]
	v_pk_mul_f32 v[36:37], v[18:19], v[42:43] op_sel_hi:[1,0]
	v_pk_mul_f32 v[20:21], v[24:25], v[182:183]
	v_pk_mul_f32 v[18:19], v[22:23], v[180:181]
	v_pk_mul_f32 v[24:25], v[34:35], v[186:187]
	v_pk_mul_f32 v[22:23], v[36:37], v[184:185]
	global_store_dwordx4 v[44:45], v[18:21], off offset:512 nt
	global_store_dwordx4 v[44:45], v[22:25], off offset:528 nt
	v_lshlrev_b64 v[26:27], 12, v[146:147]
	v_mov_b32_e32 v28, v43
	v_lshl_add_u64 v[26:27], s[28:29], 0, v[26:27]
	v_pk_mul_f32 v[16:17], v[16:17], v[28:29] op_sel_hi:[1,0]
	v_pk_mul_f32 v[14:15], v[14:15], v[28:29] op_sel_hi:[1,0]
	v_lshl_add_u64 v[26:27], v[26:27], 0, v[148:149]
	v_pk_mul_f32 v[30:31], v[12:13], v[28:29] op_sel_hi:[1,0]
	v_pk_mul_f32 v[32:33], v[10:11], v[28:29] op_sel_hi:[1,0]
	v_pk_mul_f32 v[8:9], v[8:9], v[28:29] op_sel_hi:[1,0]
	v_pk_mul_f32 v[6:7], v[6:7], v[28:29] op_sel_hi:[1,0]
	v_pk_mul_f32 v[12:13], v[174:175], v[16:17]
	v_pk_mul_f32 v[10:11], v[172:173], v[14:15]
	v_pk_mul_f32 v[16:17], v[178:179], v[30:31]
	v_pk_mul_f32 v[14:15], v[176:177], v[32:33]
	global_store_dwordx4 v[26:27], v[10:13], off nt
	global_store_dwordx4 v[26:27], v[14:17], off offset:16 nt
	v_pk_mul_f32 v[18:19], v[4:5], v[28:29] op_sel_hi:[1,0]
	v_pk_mul_f32 v[20:21], v[2:3], v[28:29] op_sel_hi:[1,0]
	v_pk_mul_f32 v[4:5], v[8:9], v[182:183]
	v_pk_mul_f32 v[2:3], v[6:7], v[180:181]
	v_pk_mul_f32 v[8:9], v[18:19], v[186:187]
	v_pk_mul_f32 v[6:7], v[20:21], v[184:185]
	global_store_dwordx4 v[26:27], v[2:5], off offset:512 nt
	global_store_dwordx4 v[26:27], v[6:9], off offset:528 nt
